# prep: rope-table item moved to a workgroup that runs only one transpose tile besides it
# baseline (speedup 1.0000x reference)
; DI void ph_prep(const Params& p, unsigned char* smem, int bid, int nb) {
;     ...
;   const int total = n_mod_items + WT_TILES + 1;
;   for (int it = bid; it < total; it += nb) {
;     if (it >= n_mod_items && it < n_mod_items + WT_TILES) {
;       wt_tile(p, 0, it - n_mod_items, smem, tid);
;     } else if (it < n_mod_items) {
.LBB0_19:
	v_readlane_b32 s1, v253, 43
	s_cmpk_eq_i32 s1, 0x200
	s_cbranch_scc0 .Lpp_std
	v_readlane_b32 s10, v253, 42
	s_nop 0
	s_cmpk_lt_u32 s10, 0xc0
	s_cbranch_scc1 .LBB0_61
	s_cmpk_eq_u32 s10, 0x1ff
	s_cbranch_scc0 .Lpp_tile
	s_cmpk_eq_u32 s0, 0x1ff
	s_cbranch_scc0 .LBB0_61
	s_movk_i32 s0, 0x620
	s_branch .LBB0_20
.Lpp_tile:
	s_addk_i32 s0, 0x13f
	s_cmpk_lt_i32 s0, 0x620
	s_cbranch_scc0 .LBB0_61
	s_branch .LBB0_20
